# ffn-in: blocks <256 run 3 paired tiles, blocks >=256 run 2 paired + 1 single tile
# baseline (speedup 1.0000x reference)
.LBB0_192:
	v_mov_b32_e32 v0, v1
	s_mul_hi_i32 s23, s22, 0x2e8ba2e9
	v_mbcnt_lo_u32_b32 v0, -1, v0
	v_mbcnt_hi_u32_b32 v0, -1, v0
	s_lshr_b32 s24, s23, 31
	s_ashr_i32 s23, s23, 3
	v_add_u32_e32 v90, s80, v0
	s_add_i32 s23, s23, s24
	s_cmpk_lt_u32 s22, 0x500
	s_cbranch_scc1 .Lffp_paired
	s_cmpk_eq_u32 s81, 0x200
	s_cbranch_scc0 .Lffp_paired
	s_sub_u32 s24, s22, 0x500
	s_lshr_b32 s98, s24, 7
	s_and_b32 s24, s24, 0x7f
	s_add_u32 s24, s24, 0x500
	s_mul_i32 s25, s24, 0x5d2
	s_lshr_b32 s25, s25, 16
	s_mul_i32 s23, s25, 44
	s_sub_u32 s24, s24, s23
	s_lshl_b32 s23, s25, 1
	s_or_b32 s23, s23, s98
	s_mul_i32 s20, s23, 44
	s_add_u32 s20, s20, s24
	s_lshl_b32 s20, s20, 6
	s_mov_b32 s99, s20
	s_mul_i32 s24, s23, 0xb00
	v_lshlrev_b32_e32 v0, 3, v90
	v_ashrrev_i32_e32 v89, 3, v90
	v_and_b32_e32 v88, 56, v0
	v_subrev_u32_e32 v0, s24, v89
	v_add_u32_e32 v0, s20, v0
	v_lshl_or_b32 v0, v0, 10, v88
	v_lshl_add_u64 v[72:73], v[0:1], 1, s[4:5]
	v_lshl_add_u32 v0, s23, 7, v89
	v_lshl_or_b32 v0, v0, 10, v88
	v_lshl_add_u64 v[74:75], v[0:1], 1, s[72:73]
	v_add_co_u32_e32 v76, vcc, s18, v74
	s_waitcnt lgkmcnt(0)
	s_nop 0
	v_addc_co_u32_e32 v77, vcc, 0, v75, vcc
	v_add_co_u32_e32 v78, vcc, s29, v74
	s_nop 0
	s_nop 0
	v_addc_co_u32_e32 v79, vcc, 0, v75, vcc
	v_add_co_u32_e32 v80, vcc, s10, v74
	s_nop 0
	s_nop 0
	v_addc_co_u32_e32 v81, vcc, 0, v75, vcc
	s_nop 0
	s_nop 0
	s_mov_b32 s24, 0x580000
	v_add_co_u32_e32 v82, vcc, s24, v72
	s_mov_b32 s24, 0x590000
	s_nop 0
	v_addc_co_u32_e32 v83, vcc, 0, v73, vcc
	v_add_co_u32_e32 v84, vcc, s18, v72
	s_nop 0
	s_nop 0
	v_addc_co_u32_e32 v85, vcc, 0, v73, vcc
	v_add_co_u32_e32 v86, vcc, s24, v72
	s_nop 0
	s_nop 0
	v_addc_co_u32_e32 v87, vcc, 0, v73, vcc
	s_nop 0
	v_mul_lo_u32 v34, v89, s27
	v_add_lshl_u32 v92, v34, v88, 1
	s_barrier
	v_and_b32_e32 v0, 31, v90
	v_add_u32_e32 v93, 0xd800, v92
	v_ashrrev_i32_e32 v2, 1, v90
	v_and_b32_e32 v91, 0xffffffc0, v2
	v_bfe_u32 v102, v90, 4, 3
	v_lshlrev_b32_e32 v102, 4, v102
	v_xor_b32_e32 v74, v102, v74
	v_xor_b32_e32 v76, v102, v76
	v_xor_b32_e32 v78, v102, v78
	v_xor_b32_e32 v80, v102, v80
	v_xor_b32_e32 v72, v102, v72
	v_xor_b32_e32 v82, v102, v82
	v_xor_b32_e32 v84, v102, v84
	v_xor_b32_e32 v86, v102, v86
	v_bfe_u32 v102, v90, 5, 1
	v_bfe_u32 v103, v90, 1, 3
	v_xor_b32_e32 v102, v102, v103
	v_lshlrev_b32_e32 v102, 4, v102
	v_lshrrev_b32_e32 v103, 1, v90
	v_and_b32_e32 v103, 64, v103
	v_and_b32_e32 v104, 31, v90
	v_or_b32_e32 v103, v103, v104
	v_lshl_or_b32 v94, v103, 7, v102
	v_and_b32_e32 v103, 0x5f, v90
	v_lshl_or_b32 v98, v103, 7, v102
	v_add_u32_e32 v98, 0x4000, v98
	v_xor_b32_e32 v95, 0x20, v94
	v_xor_b32_e32 v99, 0x20, v98
	v_xor_b32_e32 v96, 0x40, v94
	v_xor_b32_e32 v100, 0x40, v98
	v_xor_b32_e32 v97, 0x60, v94
	v_xor_b32_e32 v101, 0x60, v98
	v_mov_b32_e32 v214, 0x80
	v_mov_b32_e32 v215, 0
	s_lshl_b32 vcc_lo, s80, 4
	v_mov_b32_e32 v2, 0
	v_mov_b32_e32 v3, 0
	v_mov_b32_e32 v4, 0
	v_mov_b32_e32 v5, 0
	v_mov_b32_e32 v6, 0
	v_mov_b32_e32 v7, 0
	v_mov_b32_e32 v8, 0
	v_mov_b32_e32 v9, 0
	v_mov_b32_e32 v10, 0
	v_mov_b32_e32 v11, 0
	v_mov_b32_e32 v12, 0
	v_mov_b32_e32 v13, 0
	v_mov_b32_e32 v14, 0
	v_mov_b32_e32 v15, 0
	v_mov_b32_e32 v16, 0
	v_mov_b32_e32 v17, 0
	v_mov_b32_e32 v18, 0
	v_mov_b32_e32 v19, 0
	v_mov_b32_e32 v20, 0
	v_mov_b32_e32 v21, 0
	v_mov_b32_e32 v22, 0
	v_mov_b32_e32 v23, 0
	v_mov_b32_e32 v24, 0
	v_mov_b32_e32 v25, 0
	v_mov_b32_e32 v26, 0
	v_mov_b32_e32 v27, 0
	v_mov_b32_e32 v28, 0
	v_mov_b32_e32 v29, 0
	v_mov_b32_e32 v30, 0
	v_mov_b32_e32 v31, 0
	v_mov_b32_e32 v32, 0
	v_mov_b32_e32 v33, 0
	v_mov_b32_e32 v34, 0
	v_mov_b32_e32 v35, 0
	v_mov_b32_e32 v36, 0
	v_mov_b32_e32 v37, 0
	v_mov_b32_e32 v38, 0
	v_mov_b32_e32 v39, 0
	v_mov_b32_e32 v40, 0
	v_mov_b32_e32 v41, 0
	v_mov_b32_e32 v42, 0
	v_mov_b32_e32 v43, 0
	v_mov_b32_e32 v44, 0
	v_mov_b32_e32 v45, 0
	v_mov_b32_e32 v46, 0
	v_mov_b32_e32 v47, 0
	v_mov_b32_e32 v48, 0
	v_mov_b32_e32 v49, 0
	v_mov_b32_e32 v50, 0
	v_mov_b32_e32 v51, 0
	v_mov_b32_e32 v52, 0
	v_mov_b32_e32 v53, 0
	v_mov_b32_e32 v54, 0
	v_mov_b32_e32 v55, 0
	v_mov_b32_e32 v56, 0
	v_mov_b32_e32 v57, 0
	v_mov_b32_e32 v58, 0
	v_mov_b32_e32 v59, 0
	v_mov_b32_e32 v60, 0
	v_mov_b32_e32 v61, 0
	v_mov_b32_e32 v62, 0
	v_mov_b32_e32 v63, 0
	v_mov_b32_e32 v64, 0
	v_mov_b32_e32 v65, 0
	s_mov_b32 m0, vcc_lo
	s_nop 0
	global_load_lds_dwordx4 v[74:75], off
	s_add_u32 m0, vcc_lo, 0x1000
	s_nop 0
	global_load_lds_dwordx4 v[76:77], off
	s_add_u32 m0, vcc_lo, 0x2000
	s_nop 0
	global_load_lds_dwordx4 v[78:79], off
	s_add_u32 m0, vcc_lo, 0x3000
	s_nop 0
	global_load_lds_dwordx4 v[80:81], off
	s_add_u32 m0, vcc_lo, 0x4000
	s_nop 0
	global_load_lds_dwordx4 v[72:73], off
	s_add_u32 m0, vcc_lo, 0x5000
	s_nop 0
	global_load_lds_dwordx4 v[82:83], off
	s_add_u32 m0, vcc_lo, 0x6000
	s_nop 0
	global_load_lds_dwordx4 v[84:85], off
	s_add_u32 m0, vcc_lo, 0x7000
	s_nop 0
	global_load_lds_dwordx4 v[86:87], off
	v_lshl_add_u64 v[74:75], v[74:75], 0, v[214:215]
	v_lshl_add_u64 v[76:77], v[76:77], 0, v[214:215]
	v_lshl_add_u64 v[78:79], v[78:79], 0, v[214:215]
	v_lshl_add_u64 v[80:81], v[80:81], 0, v[214:215]
	v_lshl_add_u64 v[72:73], v[72:73], 0, v[214:215]
	v_lshl_add_u64 v[82:83], v[82:83], 0, v[214:215]
	v_lshl_add_u64 v[84:85], v[84:85], 0, v[214:215]
	v_lshl_add_u64 v[86:87], v[86:87], 0, v[214:215]
	s_add_u32 m0, vcc_lo, 0x8000
	s_nop 0
	global_load_lds_dwordx4 v[74:75], off
	s_add_u32 m0, vcc_lo, 0x9000
	s_nop 0
	global_load_lds_dwordx4 v[76:77], off
	s_add_u32 m0, vcc_lo, 0xa000
	s_nop 0
	global_load_lds_dwordx4 v[78:79], off
	s_add_u32 m0, vcc_lo, 0xb000
	s_nop 0
	global_load_lds_dwordx4 v[80:81], off
	s_add_u32 m0, vcc_lo, 0xc000
	s_nop 0
	global_load_lds_dwordx4 v[72:73], off
	s_add_u32 m0, vcc_lo, 0xd000
	s_nop 0
	global_load_lds_dwordx4 v[82:83], off
	s_add_u32 m0, vcc_lo, 0xe000
	s_nop 0
	global_load_lds_dwordx4 v[84:85], off
	s_add_u32 m0, vcc_lo, 0xf000
	s_nop 0
	global_load_lds_dwordx4 v[86:87], off
	v_lshl_add_u64 v[74:75], v[74:75], 0, v[214:215]
	v_lshl_add_u64 v[76:77], v[76:77], 0, v[214:215]
	v_lshl_add_u64 v[78:79], v[78:79], 0, v[214:215]
	v_lshl_add_u64 v[80:81], v[80:81], 0, v[214:215]
	v_lshl_add_u64 v[72:73], v[72:73], 0, v[214:215]
	v_lshl_add_u64 v[82:83], v[82:83], 0, v[214:215]
	v_lshl_add_u64 v[84:85], v[84:85], 0, v[214:215]
	v_lshl_add_u64 v[86:87], v[86:87], 0, v[214:215]
	s_mov_b32 vcc_hi, 7
	s_waitcnt vmcnt(8)
	s_barrier
	ds_read_b128 v[166:169], v94
	s_setprio 3
	ds_read_b128 v[170:173], v98
	ds_read_b128 v[174:177], v98 offset:4096
	ds_read_b128 v[178:181], v94 offset:4096
	ds_read_b128 v[182:185], v95
	ds_read_b128 v[188:191], v99
	ds_read_b128 v[192:195], v99 offset:4096
	ds_read_b128 v[206:209], v95 offset:4096
	s_waitcnt lgkmcnt(6)
	v_mfma_f32_32x32x16_bf16 v[34:49], v[166:169], v[170:173], v[34:49]
	ds_read_b128 v[236:239], v96
	s_waitcnt lgkmcnt(5)
	v_mfma_f32_32x32x16_bf16 v[2:17], v[178:181], v[170:173], v[2:17]
	ds_read_b128 v[240:243], v100
	v_mfma_f32_32x32x16_bf16 v[18:33], v[178:181], v[174:177], v[18:33]
	ds_read_b128 v[244:247], v100 offset:4096
	v_mfma_f32_32x32x16_bf16 v[50:65], v[166:169], v[174:177], v[50:65]
	ds_read_b128 v[248:251], v96 offset:4096
	s_waitcnt lgkmcnt(6)
	v_mfma_f32_32x32x16_bf16 v[34:49], v[182:185], v[188:191], v[34:49]
	ds_read_b128 v[126:129], v97
	s_waitcnt lgkmcnt(5)
	v_mfma_f32_32x32x16_bf16 v[2:17], v[206:209], v[188:191], v[2:17]
	ds_read_b128 v[130:133], v101
	v_mfma_f32_32x32x16_bf16 v[18:33], v[206:209], v[192:195], v[18:33]
	ds_read_b128 v[210:213], v101 offset:4096
	v_mfma_f32_32x32x16_bf16 v[50:65], v[182:185], v[192:195], v[50:65]
	ds_read_b128 v[222:225], v97 offset:4096
	s_waitcnt vmcnt(0) lgkmcnt(0)
	s_barrier

.Lffp_next:
	s_cmpk_eq_u32 s81, 0x200
	s_cbranch_scc0 .Lffp_next_orig
	s_add_i32 s22, s22, s81
	s_cmpk_gt_i32 s22, 0x5ff
	s_cbranch_scc0 .LBB0_192
	s_branch .Lffp_done
